# static priority raise (s_setprio 1) for waves 4-7 during the attention/GLA/conv work-queue phase, reset at phase end
# baseline (speedup 1.0000x reference)
; __device__ __forceinline__ void gla_decays_load(GlaPre& g, const Params& p, int l, size_t rowbase, int h, int tid) {
;     const float* alpha = (const float*)(p.ws + WS_ALPHA) + rowbase * 32;
; #pragma unroll
;     for (int j = 0; j < 4; ++j) { const int i = tid + 512 * j; g.al[j] = alpha[i]; const int dir = i >> 10, r = (i >> 6) & 15, d = i & 63; g.wl[j] = (dir ? p.wa_b : p.wa_f)[(size_t)l * 16 * 384 + r * 384 + h * 64 + d]; }
;     g.bsv = (((tid >> 6) & 1) ? p.ba_b : p.ba_f)[l * 384 + h * 64 + (tid & 63)];
; }
; __global__ void __launch_bounds__(512, 2) mega_fwd(Params p_unused) {
;     ...
;             const int nNA = 768 + (need_ctx ? 24 : 0), nG1 = 2 * 6 * NCH, nCV = Mrows / 64;
;             unsigned* qctr = (unsigned*)ws + 3600 + 64 * l;
;             for (;;) {
;                 __syncthreads();
;                 if (tid == 0) MISC[4] = atomicAdd(qctr, 1u);
;                 __syncthreads();
;                 const int it = (int)MISC[4];
;                 if (it >= nNA + nG1 + nCV) break;
;                 if (it < nNA) {
;                     if (it < 768) na_item(lds, P, p.rpb + (size_t)l * 6 * 465, BR, it / 384, (it >> 6) % 6, it & 63, 0, tid, wave, lane);
;                     else { const int j = it - 768; na_item(lds, P, p.rpb, BR, j / 12, (j >> 1) % 6, -1, j & 1, tid, wave, lane); }
;                 } else if (it < nNA + nG1) { const int j = it - nNA; gla1_item(lds, p, l, j / (6 * NCH), (j / NCH) % 6, j % NCH, tid, wave, lane); }
;                 else { conv_item(P, p.conv_w + l * 1536, BR, it - nNA - nG1, tid); }
.LBB0_427:
	v_writelane_b32 v242, s68, 3
	s_nop 1
	v_writelane_b32 v242, s69, 4
	s_or_b64 exec, exec, s[0:1]
	v_readlane_b32 s6, v244, 52
	v_readlane_b32 s7, v244, 53
	s_waitcnt lgkmcnt(0)
	s_barrier
	v_writelane_b32 v242, s70, 5
	s_and_b64 s[0:1], s[70:71], exec
	s_load_dwordx8 s[44:51], s[6:7], 0x48
	s_load_dwordx2 s[26:27], s[6:7], 0x68
	s_load_dwordx2 s[22:23], s[6:7], 0x78
	s_load_dwordx2 s[8:9], s[6:7], 0xc8
	s_movk_i32 s0, 0x318
	s_cselect_b32 s59, s0, 0x300
	s_movk_i32 s0, 0x108
	v_mov_b32_e32 v106, v166
	s_cselect_b32 s0, s0, 0x100
	s_add_i32 s18, s59, 0x630
	s_lshl_b32 s24, s58, 6
	v_readfirstlane_b32 s2, v106
	s_add_i32 s19, s18, s0
	s_ashr_i32 s6, s2, 6
	s_waitcnt lgkmcnt(0)
	s_add_u32 s12, s8, 0x8e00000
	s_addc_u32 s13, s9, 0
	s_add_u32 s82, s8, 0x4c00000
	s_addc_u32 s83, s9, 0
	s_lshl_b64 s[10:11], s[24:25], 2
	s_add_u32 s4, s8, s10
	s_addc_u32 s5, s9, s11
	s_mul_i32 s30, s58, 0x600
	s_mov_b32 s31, s25
	s_add_u32 s10, s4, 0x3840
	s_addc_u32 s11, s5, 0
	s_lshl_b64 s[30:31], s[30:31], 2
	v_lshlrev_b32_e32 v8, 3, v106
	s_add_u32 s30, s44, s30
	v_and_b32_e32 v1, 0x1f8, v8
	s_mul_i32 s42, s58, 0x1800
	s_addc_u32 s31, s45, s31
	v_lshlrev_b32_e32 v34, 2, v1
	v_lshl_add_u64 v[110:111], s[30:31], 0, v[34:35]
	v_lshlrev_b32_e32 v34, 1, v1
	v_bfe_u32 v1, v106, 6, 4
	s_movk_i32 s5, 0x400
	v_mov_b32_e32 v15, s42
	s_movk_i32 s4, 0x180
	v_mov_b32_e32 v9, s51
	v_mov_b32_e32 v12, s47
	v_cmp_gt_u32_e64 s[40:41], s5, v106
	v_mov_b32_e32 v13, s50
	v_mov_b32_e32 v14, s46
	v_mad_u32_u24 v4, v1, s4, v15
	v_mov_b32_e32 v5, v35
	v_writelane_b32 v242, s71, 6
	v_and_b32_e32 v10, 63, v106
	v_cndmask_b32_e64 v3, v9, v12, s[40:41]
	v_cndmask_b32_e64 v2, v13, v14, s[40:41]
	v_lshlrev_b64 v[4:5], 2, v[4:5]
	v_add_u32_e32 v16, 0x200, v106
	v_lshlrev_b32_e32 v0, 2, v10
	v_writelane_b32 v242, s42, 7
	v_lshl_add_u64 v[2:3], v[2:3], 0, v[4:5]
	v_mov_b32_e32 v1, v35
	v_bfe_u32 v6, v16, 6, 4
	v_cmp_gt_u32_e64 s[42:43], s5, v16
	v_lshl_add_u64 v[116:117], v[2:3], 0, v[0:1]
	v_mad_u32_u24 v6, v6, s4, v15
	v_cndmask_b32_e64 v3, v9, v12, s[42:43]
	v_cndmask_b32_e64 v2, v13, v14, s[42:43]
	v_mov_b32_e32 v7, v35
	s_movk_i32 s7, 0xfbff
	v_lshl_add_u64 v[2:3], v[6:7], 2, v[2:3]
	v_cmp_lt_u32_e64 s[44:45], s7, v106
	v_lshl_add_u64 v[118:119], v[2:3], 0, v[0:1]
	v_add_u32_e32 v18, 0x600, v106
	v_cndmask_b32_e64 v3, v9, v12, s[44:45]
	v_cndmask_b32_e64 v2, v13, v14, s[44:45]
	v_lshl_add_u64 v[2:3], v[2:3], 0, v[4:5]
	v_bfe_u32 v4, v18, 6, 4
	v_cmp_gt_u32_e64 s[46:47], s5, v18
	v_lshl_add_u64 v[120:121], v[2:3], 0, v[0:1]
	v_mad_u32_u24 v4, v4, s4, v15
	v_cndmask_b32_e64 v3, v9, v12, s[46:47]
	v_cndmask_b32_e64 v2, v13, v14, s[46:47]
	v_mov_b32_e32 v5, v35
	v_lshl_add_u64 v[2:3], v[4:5], 2, v[2:3]
	v_lshl_add_u64 v[122:123], v[2:3], 0, v[0:1]
	v_and_b32_e32 v2, 64, v106
	v_mov_b32_e32 v3, s27
	v_mov_b32_e32 v4, s49
	v_cmp_eq_u32_e32 vcc, 0, v2
	v_mov_b32_e32 v2, s26
	s_add_i32 s4, 0, 0x4000
	v_cndmask_b32_e32 v125, v3, v4, vcc
	v_mov_b32_e32 v3, s48
	v_bfe_u32 v4, v106, 6, 1
	v_cndmask_b32_e32 v124, v2, v3, vcc
	v_mov_b32_e32 v5, s4
	v_cmp_eq_u32_e32 vcc, 0, v4
	v_lshlrev_b32_e32 v3, 2, v106
	v_lshlrev_b32_e32 v12, 12, v4
	v_cndmask_b32_e64 v13, v5, 0, vcc
	v_cmp_gt_i32_e32 vcc, 64, v106
	v_lshlrev_b32_e32 v14, 6, v4
	s_mul_i32 s21, s58, 0x180
	v_cndmask_b32_e64 v4, v5, 0, vcc
	v_add_u32_e32 v173, v4, v0
	v_and_b32_e32 v4, 12, v3
	v_or_b32_e32 v5, 1, v4
	v_cvt_f32_ubyte0_e32 v5, v5
	v_writelane_b32 v242, s21, 8
	v_mul_f32_e32 v5, 0xbf549a78, v5
	v_and_b32_e32 v2, 28, v3
	v_writelane_b32 v242, s4, 9
	s_movk_i32 s4, 0x80
	v_exp_f32_e32 v174, v5
	v_or_b32_e32 v5, 2, v4
	v_cmp_gt_i32_e64 s[48:49], s4, v106
	v_cvt_f32_ubyte0_e32 v5, v5
	v_cmp_gt_u32_e64 s[4:5], 16, v2
	v_mul_f32_e32 v5, 0xbf549a78, v5
	v_ashrrev_i32_e32 v128, 4, v106
	v_writelane_b32 v242, s4, 10
	v_ashrrev_i32_e32 v130, 4, v16
	v_exp_f32_e32 v175, v5
	v_or_b32_e32 v5, 3, v4
	v_cvt_f32_ubyte0_e32 v4, v4
	v_writelane_b32 v242, s5, 11
	s_movk_i32 s4, 0x110
	v_mul_f32_e32 v4, 0xbf549a78, v4
	v_mul_lo_u32 v20, v128, s4
	v_mul_lo_u32 v21, v130, s4
	s_cmp_lt_u32 s6, 4
	s_mov_b32 s4, 0xe400
	v_ashrrev_i32_e32 v108, 3, v106
	v_cvt_f32_ubyte0_e32 v5, v5
	v_exp_f32_e32 v177, v4
	v_lshlrev_b32_e32 v4, 2, v2
	s_cselect_b32 s4, 0xc000, s4
	s_lshl_b32 s5, s6, 5
	v_or_b32_e32 v143, s21, v10
	v_mul_f32_e32 v5, 0xbf549a78, v5
	v_add_u32_e32 v178, 0, v4
	v_lshl_or_b32 v4, v108, 8, v4
	s_movk_i32 s21, 0x90
	s_add_i32 s4, s4, 0
	s_and_b32 s7, s5, 0x60
	v_and_b32_e32 v7, 12, v0
	v_exp_f32_e32 v176, v5
	v_add_u32_e32 v179, 0, v4
	v_mul_lo_u32 v4, v108, s21
	v_lshlrev_b32_e32 v5, 1, v2
	s_add_i32 s4, s4, s7
	v_lshlrev_b32_e32 v181, 1, v7
	v_add3_u32 v180, 0, v4, v5
	v_and_b32_e32 v22, 15, v106
	v_lshrrev_b32_e32 v5, 1, v106
	v_add_u32_e32 v24, s4, v181
	s_and_b32 s4, s5, 0xfffff80
	v_readlane_b32 s5, v243, 51
	v_and_b32_e32 v5, 24, v5
	v_bfe_u32 v23, v106, 2, 2
	v_or_b32_e32 v7, s4, v22
	s_add_i32 s4, s5, s7
	v_or_b32_e32 v6, v5, v23
	v_add_u32_e32 v27, s4, v5
	v_lshlrev_b32_e32 v5, 4, v106
	v_mul_u32_u24_e32 v25, 0x90, v6
	v_mul_u32_u24_e32 v28, 0x110, v6
	v_and_b32_e32 v6, 0x70, v5
	v_ashrrev_i32_e32 v182, 10, v106
	v_bfe_u32 v5, v106, 3, 7
	s_add_u32 s26, s8, 0x21a00000
	v_and_b32_e32 v126, 0x78, v8
	v_mul_lo_u32 v29, v7, s21
	v_lshl_or_b32 v7, v182, 7, v5
	s_addc_u32 s27, s9, 0
	v_lshlrev_b32_e32 v8, 7, v5
; #define LAS __attribute__((address_space(3)))
; __device__ __forceinline__ void na_item(LAS unsigned char* lds, const bf16* P, const float* rpb, bf16* O, int b, int h, int rp, int qhalf, int tid, int wave, int lane) {
;     LAS float* bias = (LAS float*)(lds + 69632);
;     const int fr = lane & 15, fq = lane >> 4, g = wave & 3;
;     const bool loc = rp >= 0;
;     int rA = 0, qc = 0, cs = 0, ja = 0, jb = 1, rsA = 0, kr_lo = 0, nloc = 0; size_t qrowA;
;     if (loc) { rA = 2 * rp + (wave >> 2); qc = g == 0 ? (fr < 8 ? fr : 48 + fr) : 16 * g - 8 + fr; cs = min(max(qc - 8, 0), 48); ja = g == 0 ? 0 : g - 1; jb = g == 0 ? 3 : g;
;         qrowA = (size_t)b * SEQ + rA * 64 + qc; rsA = min(max(rA - 4, 0), 120);
;         kr_lo = min(max(2 * rp - 4, 0), 120); const int kr_hi = min(max(2 * rp - 3, 0), 120) + 7; nloc = kr_hi - kr_lo + 1; }
;     else qrowA = (size_t)ML + b * CTX + 128 * qhalf + 16 * wave + fr;
; __global__ void __launch_bounds__(512, 2) mega_fwd(Params p_unused) {
;     ...
;             const int nNA = 768 + (need_ctx ? 24 : 0), nG1 = 2 * 6 * NCH, nCV = Mrows / 64;
;             unsigned* qctr = (unsigned*)ws + 3600 + 64 * l;
;             for (;;) {
;                 __syncthreads();
;                 if (tid == 0) MISC[4] = atomicAdd(qctr, 1u);
;                 __syncthreads();
;                 const int it = (int)MISC[4];
;                 if (it >= nNA + nG1 + nCV) break;
;                 if (it < nNA) {
;                     if (it < 768) na_item(lds, P, p.rpb + (size_t)l * 6 * 465, BR, it / 384, (it >> 6) % 6, it & 63, 0, tid, wave, lane);
;                     else { const int j = it - 768; na_item(lds, P, p.rpb, BR, j / 12, (j >> 1) % 6, -1, j & 1, tid, wave, lane); }
;                 } else if (it < nNA + nG1) { const int j = it - nNA; gla1_item(lds, p, l, j / (6 * NCH), (j / NCH) % 6, j % NCH, tid, wave, lane); }
;                 else { conv_item(P, p.conv_w + l * 1536, BR, it - nNA - nG1, tid); }
	v_mov_b32_e32 v9, v35
	v_mul_lo_u32 v31, v7, s21
	v_lshl_add_u64 v[8:9], s[26:27], 0, v[8:9]
	v_mov_b32_e32 v7, v35
	v_add_u32_e32 v17, 0x400, v106
	v_lshl_add_u64 v[132:133], v[8:9], 0, v[6:7]
	v_ashrrev_i32_e32 v183, 10, v16
	v_bfe_u32 v8, v16, 3, 7
	v_lshl_or_b32 v9, v183, 7, v8
	v_ashrrev_i32_e32 v184, 10, v17
	v_mul_lo_u32 v16, v9, s21
	v_lshlrev_b32_e32 v8, 7, v8
	v_mov_b32_e32 v9, v35
	v_lshl_or_b32 v5, v184, 7, v5
	v_lshl_add_u64 v[8:9], s[26:27], 0, v[8:9]
	v_mul_lo_u32 v17, v5, s21
	v_ashrrev_i32_e32 v185, 10, v18
	v_bfe_u32 v5, v18, 3, 7
	v_lshl_add_u64 v[134:135], v[8:9], 0, v[6:7]
	v_lshl_or_b32 v8, v185, 7, v5
	v_mul_lo_u32 v18, v8, s21
	v_lshlrev_b32_e32 v8, 7, v5
	v_mov_b32_e32 v9, v35
	v_add_u32_e32 v11, 0, v0
	v_add_u32_e32 v153, 0, v3
	v_add_u32_e32 v30, s5, v6
	v_lshl_add_u64 v[8:9], s[26:27], 0, v[8:9]
	v_cmp_gt_u32_e64 s[4:5], 64, v106
	v_lshl_add_u64 v[136:137], v[8:9], 0, v[6:7]
	v_add_u32_e32 v5, 0x4000, v11
	v_add_u32_e32 v6, 0x3f00, v153
	v_writelane_b32 v242, s4, 12
	s_mul_i32 s0, s58, 0xae6
	s_mov_b32 s1, s25
	v_writelane_b32 v242, s5, 13
	v_cndmask_b32_e64 v187, v5, v6, s[4:5]
	s_lshl_b32 s4, s6, 4
	s_ashr_i32 s5, s4, 31
	s_lshl_b64 s[0:1], s[0:1], 2
	v_lshl_add_u64 v[6:7], s[8:9], 0, v[0:1]
	v_bfe_u32 v1, v106, 4, 2
	v_or_b32_e32 v140, s4, v22
	s_movk_i32 s4, 0x88
	s_add_u32 s0, s22, s0
	v_lshlrev_b32_e32 v152, 2, v1
	v_mul_lo_u32 v192, v128, s4
	v_mul_lo_u32 v193, v130, s4
	s_addc_u32 s1, s23, s1
	s_and_b32 s4, s6, 3
	s_mov_b64 s[26:27], 0x900000
	v_lshlrev_b32_e32 v142, 3, v1
	v_or_b32_e32 v1, v152, v23
	s_ashr_i32 s60, s2, 8
	s_lshl_b32 s2, s4, 4
	v_cndmask_b32_e64 v15, v171, 0, vcc
	v_lshlrev_b32_e32 v4, 1, v126
	v_lshl_add_u64 v[138:139], v[6:7], 0, s[26:27]
	v_mov_b32_e32 v5, v35
	v_mul_u32_u24_e32 v190, 0x110, v1
	v_or_b32_e32 v1, 48, v10
	s_cmp_eq_u32 s4, 0
	v_subrev_co_u32_e32 v6, vcc, 8, v22
	v_mov_b32_e32 v141, s5
	v_lshl_add_u64 v[150:151], s[12:13], 0, v[4:5]
	v_mul_u32_u24_e32 v191, 0x110, v1
	v_sub_u32_e64 v5, s4, 1 clamp
	v_cndmask_b32_e32 v1, v1, v22, vcc
	v_add_u32_e32 v6, s2, v6
	s_movk_i32 s5, 0x1d1
	s_cselect_b64 vcc, -1, 0
	v_lshlrev_b32_e32 v5, 4, v5
	v_cmp_gt_i32_e64 s[62:63], s5, v106
	v_readlane_b32 s5, v243, 52
	v_cndmask_b32_e32 v154, v6, v1, vcc
	v_sub_u32_e64 v1, v154, 8 clamp
	v_add_u32_e32 v194, s5, v3
	v_or_b32_e32 v3, v5, v22
	v_mul_u32_u24_e32 v195, 0x110, v3
	v_or_b32_e32 v3, v5, v152
	v_min_u32_e32 v1, 48, v1
	v_or_b32_e32 v5, 1, v3
	v_or_b32_e32 v7, 2, v3
	v_or_b32_e32 v8, 3, v3
	v_or_b32_e32 v9, v3, v23
	v_sub_u32_e32 v3, v3, v1
	v_cmp_gt_u32_e64 s[64:65], 16, v3
	v_sub_u32_e32 v3, v5, v1
	s_and_b64 s[6:7], vcc, exec
	v_cmp_gt_u32_e64 s[66:67], 16, v3
	v_sub_u32_e32 v3, v7, v1
	s_cselect_b32 s2, 48, s2
	v_cmp_gt_u32_e64 s[68:69], 16, v3
	v_sub_u32_e32 v3, v8, v1
	v_readlane_b32 s24, v243, 50
	v_cmp_gt_u32_e64 s[70:71], 16, v3
	v_or_b32_e32 v3, s2, v22
	v_add_u32_e32 v19, s24, v4
	v_add_u32_e32 v4, 0, v4
	v_mul_u32_u24_e32 v201, 0x110, v3
	v_or_b32_e32 v3, s2, v152
	v_lshl_add_u32 v197, v192, 1, v4
	v_lshl_add_u32 v198, v193, 1, v4
	v_sub_u32_e32 v4, v3, v1
	v_cmp_gt_u32_e64 s[72:73], 16, v4
	v_or_b32_e32 v4, 1, v3
	v_sub_u32_e32 v4, v4, v1
	v_cmp_gt_u32_e64 s[74:75], 16, v4
	v_or_b32_e32 v4, 2, v3
	v_sub_u32_e32 v4, v4, v1
	v_cmp_gt_u32_e64 s[76:77], 16, v4
	v_or_b32_e32 v4, 3, v3
	v_sub_u32_e32 v1, v4, v1
	v_cmp_gt_u32_e64 s[78:79], 16, v1
	v_or_b32_e32 v1, v3, v23
	v_mul_u32_u24_e32 v202, 0x110, v1
	v_lshrrev_b32_e32 v1, 4, v108
	v_ashrrev_i32_e32 v107, 31, v106
	v_lshl_or_b32 v0, v1, 12, v0
	v_and_b32_e32 v188, 48, v106
	v_lshl_add_u64 v[4:5], v[106:107], 2, s[8:9]
	v_add_u32_e32 v107, v13, v0
	v_lshl_or_b32 v0, v1, 11, v14
	s_add_i32 s5, 0, 0x8000
	v_add_u32_e32 v203, s5, v0
	v_lshl_or_b32 v0, s4, 6, v188
	s_min_u32 s4, s4, 1
	s_lshl_b32 s4, s4, 6
	s_mov_b64 s[30:31], 0x1000
	v_lshl_add_u64 v[114:115], s[82:83], 0, v[34:35]
	v_add_u32_e32 v26, s24, v181
	v_lshl_add_u64 v[156:157], s[12:13], 0, v[34:35]
	s_mov_b64 s[6:7], 0x600000
	v_lshlrev_b32_e32 v34, 4, v22
	v_subrev_u32_e32 v204, s4, v0
	v_lshlrev_b32_e32 v0, 2, v154
	v_cmp_eq_u32_e64 s[38:39], 0, v106
	v_and_b32_e32 v127, -8, v108
	v_lshl_add_u64 v[112:113], v[110:111], 0, s[30:31]
	v_ashrrev_i32_e32 v109, 31, v108
	v_ashrrev_i32_e32 v129, 31, v128
	v_ashrrev_i32_e32 v131, 31, v130
	v_cmp_lt_i32_e64 s[50:51], 63, v106
	v_cmp_gt_u32_e64 s[52:53], 15, v2
	v_cmp_gt_u32_e64 s[54:55], 14, v2
	v_cmp_gt_u32_e64 s[56:57], 13, v2
	v_ashrrev_i32_e32 v186, 6, v106
	v_mul_u32_u24_e32 v189, 0x110, v22
	v_mul_u32_u24_e32 v196, 0x110, v9
	v_add_u32_e32 v199, 0, v188
	v_add3_u32 v200, 0, v190, v181
	v_mov_b32_e32 v155, v35
	v_lshl_add_u64 v[158:159], v[4:5], 0, s[6:7]
	v_lshl_add_u64 v[160:161], s[8:9], 0, v[34:35]
	v_sub_u32_e32 v205, 0, v0
	s_sub_i32 s61, 0, s60
	v_lshl_or_b32 v206, s2, 2, v188
	v_lshlrev_b32_e32 v162, 1, v2
	v_add_u32_e32 v207, v11, v12
	v_add_u32_e32 v208, v19, v20
	v_add_u32_e32 v209, v19, v21
	v_add_u32_e32 v210, v24, v25
	v_add_u32_e32 v211, v26, v28
	v_add_u32_e32 v212, v27, v29
	v_add_u32_e32 v213, v30, v31
	v_add_u32_e32 v214, v30, v16
	v_add_u32_e32 v215, v30, v17
	v_add_u32_e32 v216, v30, v18
	v_add_u32_e32 v217, v173, v15
	v_writelane_b32 v242, s5, 14
	v_readfirstlane_b32 s2, v166
	s_cmp_lt_u32 s2, 0x100
	s_cbranch_scc1 .Lprio_skip
	s_setprio 1
.Lprio_skip:
	s_branch .LBB0_432

; __device__ __forceinline__ void xcd_barrier(const XcdBarrier& b) {
;     asm volatile("s_waitcnt vmcnt(0)" ::: "memory");
;     __syncthreads();
;     if (threadIdx.x == 0) {
;         unsigned* bar = b.bar;
;         __builtin_amdgcn_s_waitcnt(0);
;         unsigned nloc = b.st[0], nx = b.st[1];
;         if (nloc == 0u) { xcd_barrier_complete(bar, b.x, nloc, nx); b.st[0] = nloc; b.st[1] = nx; }
.LBB0_546:
	s_setprio 0
	s_waitcnt vmcnt(0)
	v_readlane_b32 s4, v244, 0
	v_readlane_b32 s5, v244, 1
	s_waitcnt lgkmcnt(0)
	s_barrier
	s_and_saveexec_b64 s[0:1], s[4:5]
	v_readlane_b32 s38, v242, 5
	v_readlane_b32 s39, v242, 6
	s_cbranch_execz .LBB0_598
	v_readlane_b32 s2, v243, 48
	s_waitcnt vmcnt(0) expcnt(0) lgkmcnt(0)
	s_nop 0
	v_mov_b32_e32 v0, s2
	ds_read_b32 v2, v0
	v_readlane_b32 s2, v243, 49
	s_waitcnt lgkmcnt(0)
	v_cmp_ne_u32_e32 vcc, 0, v2
	v_mov_b32_e32 v0, s2
	ds_read_b32 v0, v0
	s_cbranch_vccnz .LBB0_562
	s_mov_b32 s2, 1
	s_branch .LBB0_550
